# SSD: waves with lt>=2 run the MFMA part / epilogue / state update at s_setprio 1 (partner fills gaps)
# speedup vs baseline: 1.0015x; 1.0015x over previous
; #define GAS __attribute__((address_space(1)))
; __device__ __forceinline__ void ssd_stream(const Frame& F, const Args& A, int sidx) {
;     ...
;     {
;         float* so = A.out + O_SSMP + ((size_t)(b * 32 + hd) * 64 + 32 * pt + r32) * 128 + 32 * nt + 4 * hh;
; #pragma unroll
;         for (int q4 = 0; q4 < 4; ++q4) *(GAS f32x4*)(so + 8 * q4) = (f32x4){st[4 * q4], st[4 * q4 + 1], st[4 * q4 + 2], st[4 * q4 + 3]};
;     }
;     __syncthreads();
; __device__ __forceinline__ void mixer_phase_b(const Frame& F, const Args& A) {
;     for (int s = blockIdx.x; s < 256; s += F.G) ssd_stream(F, A, s);
.LBB0_1273:
	s_setprio 0
	s_lshl_b32 s4, s4, 5
	s_or_b32 s4, s4, s62
	s_ashr_i32 s5, s4, 31
	s_lshl_b64 s[4:5], s[4:5], 6
	s_add_u32 s4, s4, s70
	s_addc_u32 s5, s5, 0
	v_or_b32_e32 v18, s4, v204
	v_mov_b32_e32 v19, s5
	v_lshlrev_b64 v[18:19], 9, v[18:19]
	v_readlane_b32 s84, v254, 33
	v_lshl_add_u64 v[18:19], s[76:77], 0, v[18:19]
	v_ashrrev_i32_e32 v151, 31, v150
	s_add_i32 s83, s83, s33
	v_readlane_b32 s85, v254, 34
	v_lshl_add_u64 v[18:19], v[150:151], 2, v[18:19]
	s_cmpk_gt_i32 s83, 0xff
	v_readlane_b32 s85, v254, 26
	global_store_dwordx4 v[18:19], v[2:5], off
	global_store_dwordx4 v[18:19], v[6:9], off offset:32
	global_store_dwordx4 v[18:19], v[10:13], off offset:64
	global_store_dwordx4 v[18:19], v[14:17], off offset:96
	s_waitcnt lgkmcnt(0)
	s_barrier
	s_cbranch_scc1 .LBB0_1316

; __device__ __forceinline__ unsigned cvt_pk_bf16(float lo, float hi) { unsigned r; asm volatile("v_cvt_pk_bf16_f32 %0, %1, %2" : "=v"(r) : "v"(lo), "v"(hi)); return r; }
; #define GAS __attribute__((address_space(1)))
; #define LAS __attribute__((address_space(3)))
; __device__ __forceinline__ void ssd_stream(const Frame& F, const Args& A, int sidx) {
;     ...
;         __syncthreads();
; #pragma unroll
;         for (int q4 = 0; q4 < 4; ++q4) { v2u o; o.x = pg8::cvt_pk_bf16(st[4 * q4], st[4 * q4 + 1]); o.y = pg8::cvt_pk_bf16(st[4 * q4 + 2], st[4 * q4 + 3]);
;             *(LAS v2u*)(ST + (32 * pt + r32) * BS_ + (32 * nt + 8 * q4 + 4 * hh) * 2) = o; }
;         {
;             const float aL = arr[127];
; #pragma unroll
;             for (int i = 0; i < 2; ++i) { *(LAS v4u*)(XST + xdst + 64 * i * XS_) = pfx[i]; if (lane < 24) *(LAS v4u*)(HAL + (3 * i + (lane >> 3)) * XS_ + 16 * (lane & 7)) = pfh[i]; }
;     ...
;         { const GAS unsigned char* zb = Zg + (size_t)t0 * 4096;
; #pragma unroll
;           for (int q4 = 0; q4 < 4; ++q4) zw[q4] = *(const GAS v2u*)(zb + 16 * q4 + zoff); }
.LBB0_1293:
	s_lshl_b32 s92, s5, 7
	s_lshl_b64 s[64:65], s[92:93], 12
	s_bitcmp1_b32 s5, 0
	s_setprio 0
	s_waitcnt lgkmcnt(0)
	s_barrier
	v_lshl_add_u64 v[198:199], v[152:153], 0, s[64:65]
	global_load_dwordx2 v[184:185], v[198:199], off
	global_load_dwordx2 v[182:183], v[198:199], off offset:16
	global_load_dwordx2 v[180:181], v[198:199], off offset:32
	global_load_dwordx2 v[178:179], v[198:199], off offset:48
	v_cvt_pk_bf16_f32 v18, v2, v3
	s_cselect_b32 s66, 0x600, 0
	v_cvt_pk_bf16_f32 v19, v4, v5
	ds_write_b64 v223, v[18:19]
	v_cvt_pk_bf16_f32 v18, v6, v7
	v_cvt_pk_bf16_f32 v19, v8, v9
	ds_write_b64 v223, v[18:19] offset:16
	v_cvt_pk_bf16_f32 v18, v10, v11
	s_add_i32 s78, s66, 0
	v_cvt_pk_bf16_f32 v19, v12, v13
	ds_write_b64 v223, v[18:19] offset:32
	v_cvt_pk_bf16_f32 v18, v14, v15
	s_add_i32 s78, s78, 0x1e400
	v_cvt_pk_bf16_f32 v19, v16, v17
	ds_write_b64 v223, v[18:19] offset:48
	v_mov_b32_e32 v18, s78
	ds_read_b32 v106, v18 offset:508
	s_waitcnt vmcnt(13)
	ds_write_b128 v229, v[50:53] offset:18432
	s_and_saveexec_b64 s[26:27], s[6:7]
	s_xor_b64 s[26:27], exec, s[26:27]
	s_cbranch_execz .LBB0_1295
	s_waitcnt vmcnt(12)
	ds_write_b128 v229, v[62:65] offset:27648

; __device__ __forceinline__ float ex2(float x) { return __builtin_amdgcn_exp2f(x); }
; #define LAS __attribute__((address_space(3)))
; #define MFMA32(a, b, c) __builtin_amdgcn_mfma_f32_32x32x16_bf16((a), (b), (c), 0, 0, 0)
; __device__ __forceinline__ void ssd_stream(const Frame& F, const Args& A, int sidx) {
;     ...
;         __syncthreads();
;         const float acs_l = arr[lcol];
;         int r32o = r32; asm volatile("" : "+v"(r32o));
;         bf16x8 cf[8], af[8];
; #pragma unroll
;         for (int s = 0; s < 8; ++s) { cf[s] = *(LAS bf16x8*)(CT + lcol * BS_ + (16 * s + 8 * hh) * 2); af[s] = *(LAS bf16x8*)(ST + (32 * pt + r32) * BS_ + (16 * s + 8 * hh) * 2); }
;         __builtin_amdgcn_sched_barrier(0);
;         f32x16 Y;
; #pragma unroll
;         for (int i = 0; i < 16; ++i) Y[i] = 0.f;
; #pragma unroll
;         for (int s = 0; s < 8; ++s) Y = MFMA32(af[s], cf[s], Y);
;         { const float el = ex2(acs_l);
; #pragma unroll
;           for (int i = 0; i < 16; ++i) Y[i] *= el; }
.LBB0_1304:
	v_lshl_add_u32 v18, v205, 2, s78
	v_mov_b32_e32 v34, v204
	v_add_u32_e32 v22, v206, v208
	s_waitcnt lgkmcnt(0)
	s_barrier
	s_cmp_gt_u32 s63, 2
	s_cbranch_scc0 .Lssd_noprio
	s_setprio 1
.Lssd_noprio:
	ds_read_b32 v140, v18
	ds_read_b128 v[98:101], v225
	ds_read_b128 v[102:105], v225 offset:32
	ds_read_b128 v[18:21], v22
	ds_read_b128 v[36:39], v22 offset:32
	ds_read_b128 v[106:109], v225 offset:64
	ds_read_b128 v[110:113], v225 offset:96
	ds_read_b128 v[40:43], v22 offset:64
	ds_read_b128 v[44:47], v22 offset:96
	ds_read_b128 v[114:117], v225 offset:128
	ds_read_b128 v[118:121], v225 offset:160
	ds_read_b128 v[130:133], v22 offset:128
	ds_read_b128 v[134:137], v22 offset:160
	ds_read_b128 v[122:125], v225 offset:192
	ds_read_b128 v[126:129], v225 offset:224
	ds_read_b128 v[186:189], v22 offset:192
	ds_read_b128 v[190:193], v22 offset:224
	s_waitcnt lgkmcnt(13)
	v_mfma_f32_32x32x16_bf16 v[18:33], v[18:21], v[98:101], 0
	s_andn2_b64 vcc, exec, s[88:89]
	s_waitcnt lgkmcnt(12)
	v_mfma_f32_32x32x16_bf16 v[18:33], v[36:39], v[102:105], v[18:33]
	v_exp_f32_e32 v36, v140
	s_waitcnt lgkmcnt(9)
	v_mfma_f32_32x32x16_bf16 v[18:33], v[40:43], v[106:109], v[18:33]
	s_waitcnt lgkmcnt(8)
	v_mfma_f32_32x32x16_bf16 v[18:33], v[44:47], v[110:113], v[18:33]
	s_waitcnt lgkmcnt(5)
	v_mfma_f32_32x32x16_bf16 v[18:33], v[130:133], v[114:117], v[18:33]
	s_waitcnt lgkmcnt(4)
	v_mfma_f32_32x32x16_bf16 v[18:33], v[134:137], v[118:121], v[18:33]
	s_waitcnt lgkmcnt(1)
	v_mfma_f32_32x32x16_bf16 v[18:33], v[186:189], v[122:125], v[18:33]
	s_waitcnt lgkmcnt(0)
	v_mfma_f32_32x32x16_bf16 v[18:33], v[190:193], v[126:129], v[18:33]
	s_nop 11
	v_pk_mul_f32 v[18:19], v[36:37], v[18:19] op_sel_hi:[0,1]
	v_pk_mul_f32 v[32:33], v[36:37], v[32:33] op_sel_hi:[0,1]
	v_pk_mul_f32 v[30:31], v[36:37], v[30:31] op_sel_hi:[0,1]
	v_pk_mul_f32 v[28:29], v[36:37], v[28:29] op_sel_hi:[0,1]
	v_pk_mul_f32 v[26:27], v[36:37], v[26:27] op_sel_hi:[0,1]
	v_pk_mul_f32 v[24:25], v[36:37], v[24:25] op_sel_hi:[0,1]
	v_pk_mul_f32 v[22:23], v[36:37], v[22:23] op_sel_hi:[0,1]
	v_pk_mul_f32 v[20:21], v[36:37], v[20:21] op_sel_hi:[0,1]
	s_cbranch_vccnz .LBB0_1312
	v_cmp_gt_i32_e64 s[26:27], v150, v34
	v_cmp_lt_i32_e64 s[28:29], v150, v34
	v_cmp_gt_i32_e64 s[30:31], v1, v34
	v_cmp_gt_i32_e64 s[34:35], v162, v34
	v_cmp_gt_i32_e64 s[36:37], v151, v34
	v_cmp_gt_i32_e64 s[38:39], v164, v34
	v_cmp_gt_i32_e64 s[40:41], v163, v34
	v_cmp_gt_i32_e64 s[42:43], v166, v34
	v_cmp_gt_i32_e64 s[44:45], v165, v34
	v_cmp_gt_i32_e64 s[46:47], v168, v34
	v_cmp_gt_i32_e64 s[48:49], v167, v34
	v_cmp_gt_i32_e64 s[50:51], v170, v34
	v_cmp_gt_i32_e64 s[52:53], v169, v34
	v_cmp_gt_i32_e64 s[54:55], v172, v34
	v_cmp_gt_i32_e64 s[56:57], v171, v34
	v_cmp_gt_i32_e64 s[58:59], v174, v34
	v_add_u32_e32 v230, s66, v208
	s_add_i32 s68, s66, 0x1e47c
	s_mov_b32 s69, 0
	v_mov_b32_e32 v231, v222
	v_mov_b32_e32 v232, v221
	ds_read_b128 v[238:241], v232
	ds_read_b128 v[244:247], v232 offset:32
	ds_read_b128 v[248:251], v232 offset:64
	s_branch .LBB0_1307
